# attention tile loop: -m_ref block no longer saved/restored (own register block for the 2nd QK chain), 32 fewer moves per 2 tiles
# speedup vs baseline: 1.0050x; 1.0033x over previous
.LBB0_416:
	v_mov_b32_e32 v1, v198
	s_load_dwordx8 s[4:11], s[0:1], 0x48
	v_and_b32_e32 v0, 63, v1
	v_lshlrev_b32_e32 v2, 2, v0
	s_cmpk_gt_i32 s3, 0x3ff
	s_waitcnt lgkmcnt(0)
	global_load_dword v3, v2, s[4:5]
	global_load_dword v4, v2, s[6:7]
	global_load_dword v5, v2, s[8:9]
	global_load_dword v6, v2, s[10:11]
	v_mbcnt_hi_u32_b32 v2, -1, v178
	v_and_b32_e32 v7, 64, v2
	v_xor_b32_e32 v8, 1, v2
	v_add_u32_e32 v7, 64, v7
	v_cmp_lt_i32_e32 vcc, v8, v7
	v_xor_b32_e32 v9, 2, v2
	v_xor_b32_e32 v10, 4, v2
	v_cndmask_b32_e32 v8, v2, v8, vcc
	v_lshlrev_b32_e32 v199, 2, v8
	v_cmp_lt_i32_e32 vcc, v9, v7
	v_xor_b32_e32 v11, 8, v2
	v_xor_b32_e32 v12, 16, v2
	v_cndmask_b32_e32 v9, v2, v9, vcc
	v_lshlrev_b32_e32 v200, 2, v9
	v_cmp_lt_i32_e32 vcc, v10, v7
	v_xor_b32_e32 v13, 32, v2
	v_readfirstlane_b32 s4, v1
	s_mov_b32 s21, 0
	s_waitcnt vmcnt(2)
	v_mul_f32_e32 v8, v3, v4
	ds_bpermute_b32 v8, v199, v8
	s_waitcnt vmcnt(0)
	v_mul_f32_e32 v14, v5, v6
	ds_bpermute_b32 v14, v199, v14
	s_waitcnt lgkmcnt(1)
	v_fmac_f32_e32 v8, v3, v4
	ds_bpermute_b32 v3, v200, v8
	s_waitcnt lgkmcnt(1)
	v_fmac_f32_e32 v14, v5, v6
	ds_bpermute_b32 v4, v200, v14
	v_cndmask_b32_e32 v5, v2, v10, vcc
	v_lshlrev_b32_e32 v201, 2, v5
	s_waitcnt lgkmcnt(1)
	v_add_f32_e32 v3, v8, v3
	ds_bpermute_b32 v5, v201, v3
	s_waitcnt lgkmcnt(1)
	v_add_f32_e32 v4, v14, v4
	ds_bpermute_b32 v6, v201, v4
	v_cmp_lt_i32_e32 vcc, v11, v7
	s_waitcnt lgkmcnt(1)
	v_add_f32_e32 v3, v3, v5
	v_cndmask_b32_e32 v8, v2, v11, vcc
	v_lshlrev_b32_e32 v202, 2, v8
	s_waitcnt lgkmcnt(0)
	v_add_f32_e32 v4, v4, v6
	ds_bpermute_b32 v5, v202, v3
	ds_bpermute_b32 v6, v202, v4
	v_cmp_lt_i32_e32 vcc, v12, v7
	s_waitcnt lgkmcnt(1)
	v_add_f32_e32 v3, v3, v5
	v_cndmask_b32_e32 v8, v2, v12, vcc
	v_lshlrev_b32_e32 v203, 2, v8
	s_waitcnt lgkmcnt(0)
	v_add_f32_e32 v4, v4, v6
	ds_bpermute_b32 v5, v203, v3
	ds_bpermute_b32 v6, v203, v4
	v_cmp_lt_i32_e32 vcc, v13, v7
	s_nop 1
	v_cndmask_b32_e32 v2, v2, v13, vcc
	v_lshlrev_b32_e32 v204, 2, v2
	s_waitcnt lgkmcnt(1)
	v_add_f32_e32 v2, v3, v5
	s_waitcnt lgkmcnt(0)
	v_add_f32_e32 v3, v4, v6
	ds_bpermute_b32 v4, v204, v2
	ds_bpermute_b32 v5, v204, v3
	s_cbranch_scc1 .LBB0_436
	s_waitcnt lgkmcnt(1)
	v_add_f32_e32 v2, v2, v4
	s_waitcnt lgkmcnt(0)
	v_add_f32_e32 v3, v3, v5
	s_load_dwordx2 s[88:89], s[0:1], 0x68
	v_lshlrev_b32_e32 v250, 4, v198
	v_cmp_gt_u32_e32 vcc, 32, v198
	s_waitcnt lgkmcnt(0)
	s_and_saveexec_b64 s[90:91], vcc
	global_load_dwordx4 v[252:255], v250, s[88:89]
	v_add_u32_e32 v250, 0x1f000, v250
	s_waitcnt vmcnt(0)
	ds_write_b128 v250, v[252:255]
	s_or_b64 exec, exec, s[90:91]
	s_waitcnt lgkmcnt(0)
	s_ashr_i32 s4, s4, 6
	v_mul_f32_e32 v2, 0x3fb8aa3b, v2
	v_mul_f32_e32 v3, 0x3fb8aa3b, v3
	s_lshl_b32 s5, s4, 3
	v_lshrrev_b32_e32 v4, 3, v0
	v_exp_f32_e32 v2, v2
	v_exp_f32_e32 v3, v3
	v_or_b32_e32 v5, s5, v4
	v_lshrrev_b32_e32 v7, 4, v0
	v_lshrrev_b32_e32 v6, 1, v5
	v_or_b32_e32 v8, s5, v7
	v_lshlrev_b32_e32 v7, 2, v7
	v_xor_b32_e32 v6, v6, v1
	v_bitop3_b32 v7, v7, v1, 12 bitop3:0x78
	v_lshlrev_b32_e32 v6, 3, v6
	v_and_or_b32 v7, v1, 3, v7
	v_lshlrev_b32_e32 v8, 10, v8
	v_lshlrev_b32_e32 v5, 10, v5
	v_sub_f32_e32 v2, v2, v3
	v_lshrrev_b32_e32 v3, 5, v0
	v_lshl_or_b32 v176, v7, 3, v8
	v_and_b32_e32 v7, 31, v1
	v_and_or_b32 v180, v6, 56, v5
	v_lshrrev_b32_e32 v6, 1, v1
	v_lshlrev_b32_e32 v5, 7, v7
	v_bfe_u32 v8, v1, 1, 3
	v_bitop3_b32 v6, v3, v6, 7 bitop3:0x78
	v_lshl_or_b32 v206, v6, 4, v5
	v_bitop3_b32 v6, v3, v8, 2 bitop3:0x36
	v_lshl_or_b32 v207, v6, 4, v5
	v_bitop3_b32 v6, v3, v8, 4 bitop3:0x36
	s_lshl_b32 s40, s4, 5
	v_lshl_or_b32 v208, v6, 4, v5
	v_bitop3_b32 v6, v3, v8, 6 bitop3:0x36
	s_lshl_b32 s42, s4, 10
	v_bfe_u32 v1, v1, 2, 2
	s_lshl_b32 s4, s4, 13
	v_lshl_or_b32 v209, v6, 4, v5
	v_and_or_b32 v4, v4, 4, v1
	v_lshlrev_b32_e32 v5, 1, v0
	v_lshlrev_b32_e32 v6, 3, v0
	s_add_i32 s4, s4, 0
	s_add_i32 s43, s42, 0
	v_lshlrev_b32_e32 v4, 8, v4
	v_and_b32_e32 v5, 32, v5
	v_and_b32_e32 v6, 24, v6
	v_lshl_add_u32 v210, v0, 2, s4
	v_lshlrev_b32_e32 v0, 4, v3
	s_add_i32 s4, s43, s42
	v_or3_b32 v4, v4, v5, v6
	v_lshlrev_b32_e32 v5, 6, v1
	v_lshl_or_b32 v0, v7, 11, v0
	v_mov_b32_e32 v1, 0
	s_add_i32 s65, s4, 0x6000
	s_add_i32 s66, s4, 0x6400
	s_add_i32 s67, s4, 0xa000
	s_add_i32 s68, s4, 0xa400
	s_movk_i32 s4, 0x80
	s_ashr_i32 s41, s40, 31
	v_lshl_add_u64 v[182:183], s[58:59], 0, v[0:1]
	v_mov_b32_e32 v181, v1
	s_add_i32 s64, s43, 0x2000
	v_lshl_add_u64 v[184:185], s[62:63], 0, v[0:1]
	v_mov_b32_e32 v177, v1
	v_mov_b32_e32 v179, v1
	v_bitop3_b32 v1, v4, s4, v5 bitop3:0x36
	s_movk_i32 s4, 0xc0
	v_add_f32_e32 v205, 0x3e4ccccd, v2
	v_lshlrev_b32_e32 v2, 3, v3
	v_or_b32_e32 v6, v4, v5
	v_bitop3_b32 v0, v4, 64, v5 bitop3:0x36
	v_bitop3_b32 v3, v4, s4, v5 bitop3:0x36
	s_add_u32 s62, s44, 0x16820000
	v_or_b32_e32 v178, 0x1000, v176
	s_addc_u32 s63, s45, 0
	s_lshl_b32 s69, s3, 4
	s_lshl_b32 s70, s46, 4
	s_mov_b64 s[22:23], 0x20000
	s_movk_i32 s71, 0x4000
	s_mov_b64 s[24:25], 0x60000
	v_mov_b32_e32 v211, 0x358637bd
	s_mov_b32 s72, 0x800000
	v_lshlrev_b32_e32 v212, 2, v2
	v_add_u32_e32 v251, 0x1f000, v212
	v_add_u32_e32 v213, 0, v6
	v_add_u32_e32 v214, 0, v0
	v_add_u32_e32 v215, 0, v1
	v_add_u32_e32 v248, 0, v3
	s_branch .LBB0_419

.LBB0_423:
	v_add_u32_e32 v81, s5, v206
	ds_read_b128 v[82:85], v81
	ds_read_b128 v[86:89], v81 offset:4096
	v_add_u32_e32 v90, s5, v207
	v_add_u32_e32 v94, s5, v208
	v_exp_f32_e32 v128, v128
	v_exp_f32_e32 v129, v129
	v_exp_f32_e32 v152, v96
	v_exp_f32_e32 v153, v97
	v_add_u32_e32 v81, s5, v209
	s_waitcnt lgkmcnt(1)
	v_mfma_f32_32x32x16_bf16 v[112:127], v[82:85], v[160:163], v[64:79]
	ds_read_b128 v[82:85], v90
	ds_read_b128 v[90:93], v90 offset:4096
	ds_read_b128 v[144:147], v94
	ds_read_b128 v[148:151], v94 offset:4096
	v_add_f32_e32 v154, v153, v152
	v_exp_f32_e32 v108, v108
	v_exp_f32_e32 v109, v109
	v_exp_f32_e32 v110, v110
	v_exp_f32_e32 v111, v111
	s_add_i32 s4, s4, 2
	s_waitcnt lgkmcnt(4)
	v_mfma_f32_32x32x16_bf16 v[216:231], v[86:89], v[160:163], v[64:79]
	ds_read_b128 v[86:89], v81
	ds_read_b128 v[94:97], v81 offset:4096
	v_add_f32_e32 v81, v129, v128
	v_add_f32_e32 v81, v154, v81
	v_add_f32_e32 v81, 0, v81
	v_cvt_pk_bf16_f32 v128, v128, v129
	s_add_i32 s5, s76, s77
	s_cmpk_eq_i32 s5, 0x2000
	s_waitcnt lgkmcnt(5)
	v_mfma_f32_32x32x16_bf16 v[112:127], v[82:85], v[164:167], v[112:127]
	v_exp_f32_e32 v83, v130
	v_exp_f32_e32 v84, v131
	v_exp_f32_e32 v85, v98
	v_exp_f32_e32 v98, v99
	v_exp_f32_e32 v99, v103
	v_cvt_pk_bf16_f32 v129, v83, v84
	v_exp_f32_e32 v103, v137
	s_waitcnt lgkmcnt(4)
	v_mfma_f32_32x32x16_bf16 v[216:231], v[90:93], v[164:167], v[216:231]
	v_add_f32_e32 v90, v84, v83
	v_add_f32_e32 v91, v98, v85
	v_add_f32_e32 v90, v91, v90
	v_add_f32_e32 v81, v90, v81
	v_exp_f32_e32 v90, v132
	v_exp_f32_e32 v91, v133
	v_exp_f32_e32 v92, v100
	v_exp_f32_e32 v93, v101
	s_waitcnt lgkmcnt(3)
	v_mfma_f32_32x32x16_bf16 v[112:127], v[144:147], v[168:171], v[112:127]
	v_cvt_pk_bf16_f32 v83, v85, v98
	v_add_f32_e32 v84, v91, v90
	v_add_f32_e32 v85, v93, v92
	v_add_f32_e32 v84, v85, v84
	v_cvt_pk_bf16_f32 v130, v90, v91
	v_exp_f32_e32 v85, v134
	v_exp_f32_e32 v90, v135
	s_waitcnt lgkmcnt(2)
	v_mfma_f32_32x32x16_bf16 v[216:231], v[148:151], v[168:171], v[216:231]
	v_exp_f32_e32 v98, v102
	v_add_f32_e32 v81, v84, v81
	v_add_f32_e32 v91, v90, v85
	v_exp_f32_e32 v102, v136
	v_exp_f32_e32 v136, v104
	v_exp_f32_e32 v137, v105
	v_cvt_pk_bf16_f32 v84, v92, v93
	s_waitcnt lgkmcnt(1)
	v_mfma_f32_32x32x16_bf16 v[112:127], v[86:89], v[172:175], v[112:127]
	v_add_f32_e32 v86, v99, v98
	v_add_f32_e32 v86, v86, v91
	v_add_f32_e32 v81, v86, v81
	ds_read_b64_tr_b16 v[86:87], v213 offset:40960
	ds_read_b64_tr_b16 v[88:89], v213 offset:43008
	v_cvt_pk_bf16_f32 v131, v85, v90
	v_add_f32_e32 v104, v103, v102
	v_add_f32_e32 v105, v137, v136
	s_waitcnt lgkmcnt(2)
	v_mfma_f32_32x32x16_bf16 v[216:231], v[94:97], v[172:175], v[216:231]
	ds_read_b64_tr_b16 v[90:91], v214 offset:40960
	ds_read_b64_tr_b16 v[92:93], v214 offset:43008
	ds_read_b64_tr_b16 v[94:95], v213 offset:45056
	ds_read_b64_tr_b16 v[96:97], v213 offset:47104
	v_cvt_pk_bf16_f32 v85, v98, v99
	v_cvt_pk_bf16_f32 v82, v152, v153
	s_cselect_b32 s8, s71, 0x2000
	s_cmpk_lg_i32 s5, 0x6000
	s_cselect_b32 s77, s8, 0
	s_add_u32 s38, s38, 0x40000
	s_waitcnt lgkmcnt(2)
	v_mfma_f32_32x32x16_bf16 v[32:47], v[90:93], v[128:131], v[32:47]
	v_add_f32_e32 v90, v105, v104
	v_add_f32_e32 v81, v90, v81
	v_cvt_pk_bf16_f32 v90, v102, v103
	v_exp_f32_e32 v91, v138
	v_exp_f32_e32 v92, v139
	v_exp_f32_e32 v138, v106
	v_exp_f32_e32 v106, v140
	v_mfma_f32_32x32x16_bf16 v[48:63], v[86:89], v[128:131], v[48:63]
	ds_read_b64_tr_b16 v[86:87], v215 offset:40960
	ds_read_b64_tr_b16 v[88:89], v215 offset:43008
	ds_read_b64_tr_b16 v[98:99], v214 offset:45056
	ds_read_b64_tr_b16 v[100:101], v214 offset:47104
	ds_read_b64_tr_b16 v[102:103], v248 offset:40960
	ds_read_b64_tr_b16 v[104:105], v248 offset:43008
	ds_read_b64_tr_b16 v[132:133], v215 offset:45056
	ds_read_b64_tr_b16 v[134:135], v215 offset:47104
	v_exp_f32_e32 v139, v107
	v_mov_b64_e32 v[158:159], v[230:231]
	s_addc_u32 s39, s39, 0
	s_add_i32 s75, s75, 0x20000
	s_and_b64 vcc, exec, s[6:7]
	s_waitcnt lgkmcnt(2)
	v_mfma_f32_32x32x16_bf16 v[0:15], v[102:105], v[128:131], v[0:15]
	v_exp_f32_e32 v102, v141
	v_exp_f32_e32 v103, v142
	v_exp_f32_e32 v104, v143
	v_add_f32_e32 v105, v92, v91
	v_cvt_pk_bf16_f32 v91, v91, v92
	v_cvt_pk_bf16_f32 v92, v106, v102
	v_cvt_pk_bf16_f32 v93, v103, v104
	v_mfma_f32_32x32x16_bf16 v[16:31], v[86:89], v[128:131], v[16:31]
	ds_read_b64_tr_b16 v[86:87], v248 offset:45056
	ds_read_b64_tr_b16 v[88:89], v248 offset:47104
	v_mov_b64_e32 v[156:157], v[228:229]
	v_mov_b64_e32 v[154:155], v[226:227]
	v_mov_b64_e32 v[152:153], v[224:225]
	v_mov_b64_e32 v[150:151], v[222:223]
	v_mov_b64_e32 v[148:149], v[220:221]
	v_mov_b64_e32 v[146:147], v[218:219]
	v_mfma_f32_32x32x16_bf16 v[48:63], v[94:97], v[90:93], v[48:63]
	v_add_f32_e32 v94, v139, v138
	v_add_f32_e32 v94, v94, v105
	v_add_f32_e32 v81, v94, v81
	v_add_f32_e32 v94, v102, v106
	v_add_f32_e32 v95, v109, v108
	v_add_f32_e32 v94, v95, v94
	v_add_f32_e32 v81, v94, v81
	v_mfma_f32_32x32x16_bf16 v[32:47], v[98:101], v[90:93], v[32:47]
	v_add_f32_e32 v94, v104, v103
	v_add_f32_e32 v95, v111, v110
	v_add_f32_e32 v94, v95, v94
	v_add_f32_e32 v106, v94, v81
	v_max_f32_e32 v81, v113, v113
	v_max_f32_e32 v94, v112, v112
	v_max_f32_e32 v81, v94, v81
	s_waitcnt lgkmcnt(2)
	v_mfma_f32_32x32x16_bf16 v[16:31], v[132:135], v[90:93], v[16:31]
	ds_read_b64_tr_b16 v[94:95], v213 offset:49152
	ds_read_b64_tr_b16 v[96:97], v213 offset:51200
	v_max3_f32 v81, v81, v114, v115
	v_max3_f32 v81, v81, v116, v117
	v_max3_f32 v81, v81, v118, v119
	v_max3_f32 v81, v81, v120, v121
	v_max3_f32 v81, v81, v122, v123
	v_max3_f32 v81, v81, v124, v125
	s_waitcnt lgkmcnt(2)
	v_mfma_f32_32x32x16_bf16 v[0:15], v[86:89], v[90:93], v[0:15]
	ds_read_b64_tr_b16 v[86:87], v214 offset:49152
	ds_read_b64_tr_b16 v[88:89], v214 offset:51200
	ds_read_b64_tr_b16 v[90:91], v213 offset:53248
	ds_read_b64_tr_b16 v[92:93], v213 offset:55296
	v_max3_f32 v81, v81, v126, v127
	v_max3_f32 v81, v81, v216, v217
	v_max3_f32 v81, v81, v218, v219
	v_max3_f32 v81, v81, v220, v221
	v_max3_f32 v81, v81, v222, v223
	v_max3_f32 v81, v81, v224, v225
	s_waitcnt lgkmcnt(4)
	v_mfma_f32_32x32x16_bf16 v[48:63], v[94:97], v[82:85], v[48:63]
	ds_read_b64_tr_b16 v[94:95], v215 offset:49152
	ds_read_b64_tr_b16 v[96:97], v215 offset:51200
	ds_read_b64_tr_b16 v[98:99], v214 offset:53248
	ds_read_b64_tr_b16 v[100:101], v214 offset:55296
	v_max3_f32 v81, v81, v226, v227
	v_max3_f32 v81, v81, v228, v229
	v_max3_f32 v107, v81, v230, v231
	v_pk_add_f32 v[196:197], v[194:195], v[106:107]
	v_mov_b64_e32 v[144:145], v[216:217]
	s_waitcnt lgkmcnt(6)
	v_mfma_f32_32x32x16_bf16 v[32:47], v[86:89], v[82:85], v[32:47]
	ds_read_b64_tr_b16 v[86:87], v248 offset:49152
	ds_read_b64_tr_b16 v[88:89], v248 offset:51200
	ds_read_b64_tr_b16 v[102:103], v215 offset:53248
	ds_read_b64_tr_b16 v[104:105], v215 offset:55296
	s_waitcnt lgkmcnt(6)
	v_mfma_f32_32x32x16_bf16 v[16:31], v[94:97], v[82:85], v[16:31]
	ds_read_b64_tr_b16 v[94:95], v248 offset:53248
	ds_read_b64_tr_b16 v[96:97], v248 offset:55296
	s_waitcnt vmcnt(0)
	s_waitcnt lgkmcnt(4)
	v_mfma_f32_32x32x16_bf16 v[0:15], v[86:89], v[82:85], v[0:15]
	v_cvt_pk_bf16_f32 v85, v110, v111
	v_cvt_pk_bf16_f32 v84, v108, v109
	v_cvt_pk_bf16_f32 v83, v138, v139
	v_cvt_pk_bf16_f32 v82, v136, v137
	v_mfma_f32_32x32x16_bf16 v[48:63], v[90:93], v[82:85], v[48:63]
	s_waitcnt lgkmcnt(0)
	s_barrier
	v_mfma_f32_32x32x16_bf16 v[32:47], v[98:101], v[82:85], v[32:47]
	v_mfma_f32_32x32x16_bf16 v[16:31], v[102:105], v[82:85], v[16:31]
	v_mfma_f32_32x32x16_bf16 v[0:15], v[94:97], v[82:85], v[0:15]
	s_cbranch_vccnz .LBB0_432

.LBB0_429:
	s_add_i32 s8, s76, 0
	v_add_u32_e32 v86, s8, v206
	ds_read_b128 v[82:85], v86
	ds_read_b128 v[86:89], v86 offset:4096
	v_add_u32_e32 v90, s8, v207
	v_add_u32_e32 v94, s8, v208
	v_add_u32_e32 v194, s8, v209
	s_waitcnt lgkmcnt(1)
	v_mfma_f32_32x32x16_bf16 v[128:143], v[82:85], v[160:163], v[64:79]
	ds_read_b128 v[82:85], v90
	ds_read_b128 v[90:93], v90 offset:4096
	v_exp_f32_e32 v95, v112
	v_exp_f32_e32 v245, v113
	v_exp_f32_e32 v145, v145
	v_exp_f32_e32 v244, v115
	v_exp_f32_e32 v115, v149
	v_cvt_pk_bf16_f32 v112, v95, v245
	s_waitcnt lgkmcnt(2)
	v_mfma_f32_32x32x16_bf16 v[96:111], v[86:89], v[160:163], v[64:79]
	ds_read_b128 v[86:89], v94
	ds_read_b128 v[232:235], v94 offset:4096
	ds_read_b128 v[236:239], v194
	ds_read_b128 v[240:243], v194 offset:4096
	v_exp_f32_e32 v94, v114
	v_exp_f32_e32 v114, v117
	v_exp_f32_e32 v156, v156
	s_add_i32 s8, s77, s76
	v_cvt_pk_bf16_f32 v113, v94, v244
	s_cmpk_eq_i32 s8, 0x2000
	s_waitcnt lgkmcnt(5)
	v_mfma_f32_32x32x16_bf16 v[128:143], v[82:85], v[164:167], v[128:143]
	v_exp_f32_e32 v85, v144
	v_exp_f32_e32 v84, v146
	v_exp_f32_e32 v144, v147
	s_cselect_b32 s9, s71, 0x2000
	v_cvt_pk_bf16_f32 v82, v85, v145
	s_cmpk_lg_i32 s8, 0x6000
	s_cselect_b32 s76, s9, 0
	s_waitcnt lgkmcnt(4)
	v_mfma_f32_32x32x16_bf16 v[96:111], v[90:93], v[164:167], v[96:111]
	v_add_f32_e64 v90, v94, v244
	v_add_f32_e64 v91, v95, v245
	v_add_f32_e64 v92, v84, v144
	v_add_f32_e64 v93, v85, v145
	v_exp_f32_e32 v94, v120
	v_pk_add_f32 v[90:91], v[90:91], v[92:93]
	v_exp_f32_e32 v92, v116
	v_exp_f32_e32 v93, v148
	v_add_f32_e32 v83, 0, v91
	s_waitcnt lgkmcnt(3)
	v_mfma_f32_32x32x16_bf16 v[128:143], v[86:89], v[168:171], v[128:143]
	v_add_f32_e32 v87, v90, v83
	v_cvt_pk_bf16_f32 v83, v84, v144
	v_add_f32_e64 v84, v92, v114
	v_add_f32_e64 v85, v93, v115
	v_exp_f32_e32 v86, v119
	v_pk_add_f32 v[88:89], v[84:85], v[84:85] op_sel_hi:[0,1]
	v_exp_f32_e32 v85, v118
	v_exp_f32_e32 v88, v150
	v_exp_f32_e32 v90, v151
	s_waitcnt lgkmcnt(2)
	v_mfma_f32_32x32x16_bf16 v[96:111], v[232:235], v[168:171], v[96:111]
	v_cvt_pk_bf16_f32 v114, v92, v114
	v_cvt_pk_bf16_f32 v84, v93, v115
	v_add_f32_e32 v95, v85, v86
	v_add_f32_e32 v233, v88, v90
	v_cvt_pk_bf16_f32 v115, v85, v86
	v_cvt_pk_bf16_f32 v85, v88, v90
	ds_read_b64_tr_b16 v[90:91], v213 offset:24576
	ds_read_b64_tr_b16 v[92:93], v213 offset:26624
	v_exp_f32_e32 v232, v121
	v_exp_f32_e32 v88, v152
	v_exp_f32_e32 v86, v153
	ds_read_b64_tr_b16 v[116:117], v214 offset:24576
	ds_read_b64_tr_b16 v[118:119], v214 offset:26624
	ds_read_b64_tr_b16 v[144:145], v213 offset:28672
	ds_read_b64_tr_b16 v[146:147], v213 offset:30720
	v_pk_add_f32 v[120:121], v[94:95], v[232:233]
	s_waitcnt lgkmcnt(4)
	v_mfma_f32_32x32x16_bf16 v[48:63], v[90:93], v[112:115], v[48:63]
	v_add_f32_e64 v90, v88, v86
	v_add_f32_e64 v91, v89, v87
	v_exp_f32_e32 v234, v122
	v_pk_add_f32 v[152:153], v[120:121], v[90:91]
	ds_read_b64_tr_b16 v[90:91], v215 offset:24576
	ds_read_b64_tr_b16 v[92:93], v215 offset:26624
	ds_read_b64_tr_b16 v[148:149], v214 offset:28672
	ds_read_b64_tr_b16 v[150:151], v214 offset:30720
	v_exp_f32_e32 v235, v154
	v_exp_f32_e32 v87, v124
	v_exp_f32_e32 v89, v125
	v_mfma_f32_32x32x16_bf16 v[128:143], v[236:239], v[172:175], v[128:143]
	v_exp_f32_e32 v236, v123
	v_exp_f32_e32 v237, v155
	v_pk_add_f32 v[238:239], v[152:153], v[152:153] op_sel_hi:[0,1]
	v_exp_f32_e32 v238, v159
	s_min_u32 s8, s4, 32
	s_min_u32 s10, s4, 33
	s_lshl_b32 s8, s8, 17
	s_waitcnt lgkmcnt(6)
	v_mfma_f32_32x32x16_bf16 v[32:47], v[116:119], v[112:115], v[32:47]
	ds_read_b64_tr_b16 v[116:117], v248 offset:24576
	ds_read_b64_tr_b16 v[118:119], v248 offset:26624
	ds_read_b64_tr_b16 v[120:121], v215 offset:28672
	ds_read_b64_tr_b16 v[122:123], v215 offset:30720
	ds_read_b64_tr_b16 v[152:153], v248 offset:28672
	ds_read_b64_tr_b16 v[154:155], v248 offset:30720
	s_add_u32 s8, s36, s8
	s_addc_u32 s9, s37, 0
	s_waitcnt lgkmcnt(8)
	v_mfma_f32_32x32x16_bf16 v[16:31], v[90:93], v[112:115], v[16:31]
	v_add_f32_e64 v92, v234, v236
	v_add_f32_e64 v93, v235, v237
	v_cvt_pk_bf16_f32 v90, v94, v232
	v_add_f32_e64 v94, v92, v92
	v_add_f32_e64 v95, v92, v93
	v_cvt_pk_bf16_f32 v91, v234, v236
	v_cvt_pk_bf16_f32 v92, v87, v89
	v_exp_f32_e32 v94, v158
	s_waitcnt lgkmcnt(4)
	v_mfma_f32_32x32x16_bf16 v[0:15], v[116:119], v[112:115], v[0:15]
	v_exp_f32_e32 v112, v126
	v_exp_f32_e32 v114, v127
	v_add_f32_e32 v113, v87, v89
	v_max_f32_e32 v89, v128, v128
	v_cvt_pk_bf16_f32 v93, v112, v114
	s_nop 1
	v_mfma_f32_32x32x16_bf16 v[48:63], v[144:147], v[90:93], v[48:63]
	v_exp_f32_e32 v144, v157
	v_cvt_pk_bf16_f32 v147, v94, v238
	v_cvt_pk_bf16_f32 v145, v235, v237
	v_add_f32_e32 v115, v156, v144
	v_pk_add_f32 v[112:113], v[112:113], v[114:115]
	v_pk_add_f32 v[114:115], v[94:95], v[238:239]
	v_mfma_f32_32x32x16_bf16 v[32:47], v[148:151], v[90:93], v[32:47]
	v_add_f32_e64 v112, v112, v114
	v_add_f32_e64 v113, v113, v115
	v_cvt_pk_bf16_f32 v146, v156, v144
	v_add_f32_e32 v87, v112, v113
	ds_read_b64_tr_b16 v[112:113], v213 offset:32768
	ds_read_b64_tr_b16 v[114:115], v213 offset:34816
	v_add_f32_e32 v194, v196, v87
	v_max_f32_e32 v87, v129, v129
	v_max_f32_e32 v87, v89, v87
	s_waitcnt lgkmcnt(4)
	v_mfma_f32_32x32x16_bf16 v[16:31], v[120:123], v[90:93], v[16:31]
	v_max3_f32 v87, v87, v130, v131
	v_max3_f32 v87, v87, v132, v133
	v_max3_f32 v87, v87, v134, v135
	v_max3_f32 v87, v87, v136, v137
	v_max3_f32 v87, v87, v138, v139
	v_max3_f32 v87, v87, v140, v141
	v_max3_f32 v87, v87, v142, v143
	s_waitcnt lgkmcnt(2)
	v_mfma_f32_32x32x16_bf16 v[0:15], v[152:155], v[90:93], v[0:15]
	ds_read_b64_tr_b16 v[90:91], v214 offset:32768
	ds_read_b64_tr_b16 v[92:93], v214 offset:34816
	ds_read_b64_tr_b16 v[116:117], v213 offset:36864
	ds_read_b64_tr_b16 v[118:119], v213 offset:38912
	v_cvt_pk_bf16_f32 v144, v88, v86
	s_waitcnt lgkmcnt(4)
	v_mfma_f32_32x32x16_bf16 v[48:63], v[112:115], v[82:85], v[48:63]
	ds_read_b64_tr_b16 v[112:113], v215 offset:32768
	ds_read_b64_tr_b16 v[114:115], v215 offset:34816
	ds_read_b64_tr_b16 v[120:121], v214 offset:36864
	ds_read_b64_tr_b16 v[122:123], v214 offset:38912
	s_waitcnt lgkmcnt(6)
	v_mfma_f32_32x32x16_bf16 v[32:47], v[90:93], v[82:85], v[32:47]
	ds_read_b64_tr_b16 v[90:91], v248 offset:32768
	ds_read_b64_tr_b16 v[92:93], v248 offset:34816
	ds_read_b64_tr_b16 v[124:125], v215 offset:36864
	ds_read_b64_tr_b16 v[126:127], v215 offset:38912
	v_mfma_f32_32x32x16_bf16 v[96:111], v[240:243], v[172:175], v[96:111]
	s_waitcnt lgkmcnt(6)
	v_mfma_f32_32x32x16_bf16 v[16:31], v[112:115], v[82:85], v[16:31]
	ds_read_b64_tr_b16 v[112:113], v248 offset:36864
	ds_read_b64_tr_b16 v[114:115], v248 offset:38912
	s_nop 7
	v_max3_f32 v87, v87, v96, v97
	v_max3_f32 v87, v87, v98, v99
	s_waitcnt vmcnt(0)
	s_waitcnt lgkmcnt(0)
	s_barrier
	v_mfma_f32_32x32x16_bf16 v[0:15], v[90:93], v[82:85], v[0:15]
	v_lshl_add_u64 v[82:83], v[180:181], 1, s[8:9]
	s_add_i32 s8, s43, s76
	v_lshl_add_u64 v[82:83], v[82:83], 0, s[24:25]
	s_mov_b32 s9, m0
	s_mov_b32 m0, s8
	s_nop 0
	global_load_lds_dwordx4 v[82:83], off
	s_mov_b32 m0, s9
	s_lshl_b32 s8, s10, 17
	v_max3_f32 v87, v87, v100, v101
	s_add_u32 s8, s26, s8
	v_mfma_f32_32x32x16_bf16 v[48:63], v[116:119], v[144:147], v[48:63]
	v_max3_f32 v87, v87, v102, v103
	s_addc_u32 s9, s27, 0
	v_max3_f32 v87, v87, v104, v105
	s_add_u32 s8, s8, 0x40000
	v_max3_f32 v87, v87, v106, v107
	s_addc_u32 s9, s9, 0
	v_max3_f32 v87, v87, v108, v109
	v_mfma_f32_32x32x16_bf16 v[32:47], v[120:123], v[144:147], v[32:47]
	v_lshl_add_u64 v[82:83], v[176:177], 1, s[8:9]
	s_mov_b32 s10, m0
	s_mov_b32 m0, s65
	s_nop 0
	global_load_lds_dwordx4 v[82:83], off
	s_mov_b32 m0, s10
	v_max3_f32 v87, v87, v110, v111
	v_lshl_add_u64 v[82:83], v[178:179], 1, s[8:9]
	s_mov_b32 s8, m0
	s_mov_b32 m0, s66
	s_nop 0
	global_load_lds_dwordx4 v[82:83], off
	s_mov_b32 m0, s8
	v_add_f32_e32 v87, v195, v87
	v_cmp_gt_f32_e32 vcc, v87, v81
	v_mfma_f32_32x32x16_bf16 v[16:31], v[124:127], v[144:147], v[16:31]
	v_mfma_f32_32x32x16_bf16 v[0:15], v[112:115], v[144:147], v[0:15]
	s_cbranch_vccz .LBB0_423
	ds_bpermute_b32 v82, v204, v87
	v_max_f32_e32 v83, v87, v87
	s_waitcnt lgkmcnt(0)
	v_max_f32_e32 v82, v82, v82
	v_max_f32_e32 v112, v83, v82
	v_cmp_gt_f32_e32 vcc, v112, v81
	s_and_saveexec_b64 s[8:9], vcc
	s_cbranch_execz .LBB0_422
	v_sub_f32_e32 v65, v112, v195
	v_exp_f32_e64 v64, -v65
	v_xor_b32_e32 v80, 0x80000000, v112
	v_mov_b32_e32 v81, v80
	v_sub_f32_e32 v128, v128, v65
	v_mul_f32_e32 v194, v194, v64
	v_pk_mul_f32 v[62:63], v[62:63], v[64:65] op_sel_hi:[1,0]
	v_pk_mul_f32 v[60:61], v[60:61], v[64:65] op_sel_hi:[1,0]
	v_pk_mul_f32 v[58:59], v[58:59], v[64:65] op_sel_hi:[1,0]
	v_pk_mul_f32 v[56:57], v[56:57], v[64:65] op_sel_hi:[1,0]
	v_pk_mul_f32 v[54:55], v[54:55], v[64:65] op_sel_hi:[1,0]
	v_pk_mul_f32 v[52:53], v[52:53], v[64:65] op_sel_hi:[1,0]
	v_pk_mul_f32 v[50:51], v[50:51], v[64:65] op_sel_hi:[1,0]
	v_pk_mul_f32 v[48:49], v[48:49], v[64:65] op_sel_hi:[1,0]
	v_pk_mul_f32 v[46:47], v[46:47], v[64:65] op_sel_hi:[1,0]
	v_pk_mul_f32 v[44:45], v[44:45], v[64:65] op_sel_hi:[1,0]
	v_pk_mul_f32 v[42:43], v[42:43], v[64:65] op_sel_hi:[1,0]
	v_pk_mul_f32 v[40:41], v[40:41], v[64:65] op_sel_hi:[1,0]
	v_pk_mul_f32 v[38:39], v[38:39], v[64:65] op_sel_hi:[1,0]
	v_pk_mul_f32 v[36:37], v[36:37], v[64:65] op_sel_hi:[1,0]
	v_pk_mul_f32 v[34:35], v[34:35], v[64:65] op_sel_hi:[1,0]
	v_pk_mul_f32 v[32:33], v[32:33], v[64:65] op_sel_hi:[1,0]
	v_pk_mul_f32 v[30:31], v[30:31], v[64:65] op_sel_hi:[1,0]
	v_pk_mul_f32 v[28:29], v[28:29], v[64:65] op_sel_hi:[1,0]
	v_pk_mul_f32 v[26:27], v[26:27], v[64:65] op_sel_hi:[1,0]
	v_pk_mul_f32 v[24:25], v[24:25], v[64:65] op_sel_hi:[1,0]
	v_pk_mul_f32 v[22:23], v[22:23], v[64:65] op_sel_hi:[1,0]
	v_pk_mul_f32 v[20:21], v[20:21], v[64:65] op_sel_hi:[1,0]
	v_pk_mul_f32 v[18:19], v[18:19], v[64:65] op_sel_hi:[1,0]
	v_pk_mul_f32 v[16:17], v[16:17], v[64:65] op_sel_hi:[1,0]
	v_pk_mul_f32 v[14:15], v[14:15], v[64:65] op_sel_hi:[1,0]
	v_pk_mul_f32 v[12:13], v[12:13], v[64:65] op_sel_hi:[1,0]
	v_pk_mul_f32 v[10:11], v[10:11], v[64:65] op_sel_hi:[1,0]
	v_pk_mul_f32 v[8:9], v[8:9], v[64:65] op_sel_hi:[1,0]
	v_pk_mul_f32 v[6:7], v[6:7], v[64:65] op_sel_hi:[1,0]
	v_pk_mul_f32 v[4:5], v[4:5], v[64:65] op_sel_hi:[1,0]
	v_pk_mul_f32 v[2:3], v[2:3], v[64:65] op_sel_hi:[1,0]
	v_pk_mul_f32 v[0:1], v[0:1], v[64:65] op_sel_hi:[1,0]
	v_sub_f32_e32 v129, v129, v65
	v_sub_f32_e32 v130, v130, v65
	v_sub_f32_e32 v131, v131, v65
	v_sub_f32_e32 v132, v132, v65
	v_sub_f32_e32 v133, v133, v65
	v_sub_f32_e32 v134, v134, v65
	v_sub_f32_e32 v135, v135, v65
	v_sub_f32_e32 v136, v136, v65
	v_sub_f32_e32 v137, v137, v65
	v_sub_f32_e32 v138, v138, v65
	v_sub_f32_e32 v139, v139, v65
	v_sub_f32_e32 v140, v140, v65
	v_sub_f32_e32 v141, v141, v65
	v_sub_f32_e32 v142, v142, v65
	v_sub_f32_e32 v143, v143, v65
	v_sub_f32_e32 v96, v96, v65
	v_sub_f32_e32 v97, v97, v65
	v_sub_f32_e32 v98, v98, v65
	v_sub_f32_e32 v99, v99, v65
	v_sub_f32_e32 v100, v100, v65
	v_sub_f32_e32 v101, v101, v65
	v_sub_f32_e32 v102, v102, v65
	v_sub_f32_e32 v103, v103, v65
	v_sub_f32_e32 v104, v104, v65
	v_sub_f32_e32 v105, v105, v65
	v_sub_f32_e32 v106, v106, v65
	v_sub_f32_e32 v107, v107, v65
	v_sub_f32_e32 v108, v108, v65
	v_sub_f32_e32 v109, v109, v65
	v_sub_f32_e32 v110, v110, v65
	v_sub_f32_e32 v111, v111, v65
	v_mov_b32_e32 v82, v80
	v_mov_b32_e32 v83, v80
	v_mov_b32_e32 v84, v80
	v_mov_b32_e32 v85, v80
	v_mov_b32_e32 v86, v80
	v_mov_b32_e32 v87, v80
	v_mov_b32_e32 v88, v80
	v_mov_b32_e32 v89, v80
	v_mov_b32_e32 v90, v80
	v_mov_b32_e32 v91, v80
	v_mov_b32_e32 v92, v80
	v_mov_b32_e32 v93, v80
	v_mov_b32_e32 v94, v80
	v_mov_b32_e32 v95, v80
	v_mov_b64_e32 v[64:65], v[80:81]
	v_mov_b32_e32 v195, v112
	v_mov_b64_e32 v[66:67], v[82:83]
	v_mov_b64_e32 v[68:69], v[84:85]
	v_mov_b64_e32 v[70:71], v[86:87]
	v_mov_b64_e32 v[72:73], v[88:89]
	v_mov_b64_e32 v[74:75], v[90:91]
	v_mov_b64_e32 v[76:77], v[92:93]
	v_mov_b64_e32 v[78:79], v[94:95]
	s_branch .LBB0_422
